# v72 + diff/fox stage prefetch addresses via SALU 64-bit add + v_lshl_add_u64 (no carry-chain nops)
# baseline (speedup 1.0000x reference)
; #define DF_LOAD(T) do { const bf16* kg = Kb + (tokb + 128 * (T) + krow0) * 1024 + kgcol; const bf16* vg = Vb + (tokb + 128 * (T) + vkey0) * 1024 + vgcol; \
;         _Pragma("unroll") for (int c_ = 0; c_ < 4; ++c_) { kreg[c_] = *(const u32x4*)(kg + c_ * 8 * 1024); vreg[c_] = *(const u32x4*)(vg + c_ * 16 * 1024); } } while (0)
; #define DF_STORE(sb) do { LAS unsigned char* s_ = lds + (sb) * DST; \
;         _Pragma("unroll") for (int c_ = 0; c_ < 4; ++c_) { *(LAS u32x4*)(s_ + klds + c_ * 8 * 144) = kreg[c_]; *(LAS u32x4*)(s_ + vlds + c_ * 1024) = vreg[c_]; } } while (0)
; __device__ __forceinline__ void diff_phase(LAS unsigned char* lds, int L) {
;     ...
;         DF_LOAD(NT - 1); DF_STORE(0);
;         __syncthreads();
;         asm volatile("" :: "v"(qr[0]), "v"(qr[1]), "v"(qr[2]), "v"(qr[3]));
;         for (int it = 0; it < NT; ++it) {
;             const int T = NT - 1 - it;
;             if (it + 1 < NT) DF_LOAD(T - 1);
.LBB0_186:
	s_cmp_lt_u32 s52, s35
	s_cselect_b64 s[30:31], -1, 0
	s_cmp_ge_u32 s52, s35
	s_cbranch_scc1 .LBB0_188
	s_add_u32 s44, s28, 0xe3c0000
	s_addc_u32 s45, s29, 0
	v_lshl_add_u64 v[6:7], s[44:45], 0, v[190:191]
	s_add_u32 s44, s28, 0x123c0000
	s_addc_u32 s45, s29, 0
	v_lshl_add_u64 v[8:9], s[44:45], 0, v[192:193]
	global_load_dwordx4 v[128:131], v[6:7], off
	global_load_dwordx4 v[132:135], v[8:9], off
	s_add_u32 s44, s28, 0xe3c4000
	s_addc_u32 s45, s29, 0
	v_lshl_add_u64 v[6:7], s[44:45], 0, v[190:191]
	s_add_u32 s44, s28, 0x123c8000
	s_addc_u32 s45, s29, 0
	v_lshl_add_u64 v[8:9], s[44:45], 0, v[192:193]
	global_load_dwordx4 v[140:143], v[6:7], off
	global_load_dwordx4 v[156:159], v[8:9], off
	s_add_u32 s44, s28, 0xe3c8000
	s_addc_u32 s45, s29, 0
	v_lshl_add_u64 v[6:7], s[44:45], 0, v[190:191]
	s_add_u32 s44, s28, 0x123d0000
	s_addc_u32 s45, s29, 0
	v_lshl_add_u64 v[8:9], s[44:45], 0, v[192:193]
	global_load_dwordx4 v[160:163], v[6:7], off
	global_load_dwordx4 v[164:167], v[8:9], off
	s_add_u32 s44, s28, 0xe3cc000
	s_addc_u32 s45, s29, 0
	v_lshl_add_u64 v[6:7], s[44:45], 0, v[190:191]
	s_add_u32 s44, s28, 0x123d8000
	s_addc_u32 s45, s29, 0
	v_lshl_add_u64 v[8:9], s[44:45], 0, v[192:193]
	global_load_dwordx4 v[168:171], v[6:7], off
	global_load_dwordx4 v[172:175], v[8:9], off

; #define FOX_LOAD(T) do { const bf16* kg = Kb + (tokb + 128 * (T) + kvs) * 1024 + col + 8 * ch; const bf16* vg = Vb + (tokb + 128 * (T) + vkey0) * 1024 + col + vcol0; \
;         kreg[0] = *(const u32x4*)(kg); kreg[1] = *(const u32x4*)(kg + 64 * 1024); vreg[0] = *(const u32x4*)(vg); vreg[1] = *(const u32x4*)(vg + 16 * 1024); \
;         if (tid < 128) creg = clp[128 * (T) + tid] + pre[(T)]; } while (0)
; __device__ __forceinline__ void fox_phase(LAS unsigned char* lds, int L) {
;     ...
;         FOX_LOAD(NT - 1); FOX_STORE(0);
;         __syncthreads();
;         asm volatile("" :: "v"(qr[0]), "v"(qr[1]), "v"(qr[2]), "v"(qr[3]));
;         for (int it = 0; it < NT; ++it) {
;             const int T = NT - 1 - it;
;             if (it + 1 < NT) FOX_LOAD(T - 1);
.LBB0_227:
	s_add_i32 s43, s3, 1
	s_cmp_lt_u32 s43, s38
	s_cselect_b64 s[22:23], -1, 0
	s_cmp_ge_u32 s43, s38
	s_cbranch_scc1 .LBB0_231
	s_add_u32 s44, s72, 0xe400000
	s_addc_u32 s45, s73, 0
	v_lshl_add_u64 v[6:7], v[160:161], 0, s[44:45]
	global_load_dwordx4 v[116:119], v[6:7], off offset:1024
	s_add_u32 s44, s72, 0xe420000
	s_addc_u32 s45, s73, 0
	v_lshl_add_u64 v[0:1], v[160:161], 0, s[44:45]
	global_load_dwordx4 v[120:123], v[0:1], off offset:1024
	s_add_u32 s44, s72, 0x12400000
	s_addc_u32 s45, s73, 0
	v_lshl_add_u64 v[6:7], v[158:159], 0, s[44:45]
	global_load_dwordx4 v[124:127], v[6:7], off offset:1024
	s_add_u32 s44, s72, 0x12408000
	s_addc_u32 s45, s73, 0
	v_lshl_add_u64 v[0:1], v[158:159], 0, s[44:45]
	global_load_dwordx4 v[128:131], v[0:1], off offset:1024
	s_and_saveexec_b64 s[24:25], s[4:5]
	s_cbranch_execz .LBB0_230
	v_add_u32_e32 v0, s36, v183
	v_ashrrev_i32_e32 v1, 31, v0
	v_lshl_add_u64 v[0:1], v[0:1], 2, s[20:21]
	global_load_dword v0, v[0:1], off
	v_mov_b32_e32 v1, s40
	ds_read_b32 v1, v1
	s_waitcnt vmcnt(0) lgkmcnt(0)
	v_add_f32_e32 v179, v0, v1
